# also: attention K loads batched, per-unit vmcnt(0) drain before K-loop removed
# speedup vs baseline: 1.0055x; 1.0055x over previous
; #define LAS __attribute__((address_space(3)))
; __device__ __forceinline__ int bid_fresh() { int b = blockIdx.x; asm volatile("" : "+s"(b)); return b; }
; __device__ __forceinline__ void attn_phase(const Params& p, LAS unsigned char* lds) {
;     ...
;     for (int unit = bid_fresh(); unit < 3072; unit += G) {
;         const int g = unit >> 10, rem = unit & 1023, h = rem >> 7, rb = rem & 127;
;         const int dsh = 2 * g, d = 1 << dsh, r = rb & (d - 1), blk = rb >> dsh, i0 = blk * 128;
;         const int col_q = g * 1024 + h * 128, col_k = 3072 + col_q, col_v = 6144 + col_q;
;         bf16x8 Qf[4];
;         { const size_t tq = (size_t)(r + d * (i0 + wid * 16 + fr));
; #pragma unroll
;           for (int ks = 0; ks < 4; ++ks) Qf[ks] = *(const bf16x8*)(qkv + tq * 9216 + col_q + ks * 32 + fq * 8); }
; #pragma unroll
;         for (int i = 0; i < 8; ++i) {
;             const int cid = tid + 512 * i, key = cid >> 4, dc = cid & 15, kk = i0 - 128 + key;
;             u32x4 v = (u32x4){0u, 0u, 0u, 0u};
;             if (kk >= 0) v = *(const u32x4*)(qkv + (size_t)(r + d * kk) * 9216 + col_k + dc * 8);
;             *(LAS u32x4*)(KL + key * 136 + dc * 8) = v;
;         }
;         const int keyb = tid >> 4, db = tid & 15;
;         u32x4 vin[8];
; #pragma unroll
;         for (int i = 0; i < 8; ++i) {
;             const int kk = i0 - 128 + keyb * 8 + i;
;             vin[i] = (u32x4){0u, 0u, 0u, 0u};
;             if (kk >= 0) vin[i] = *(const u32x4*)(qkv + (size_t)(r + d * kk) * 9216 + col_v + db * 8);
;         }
.LBB0_178:
	s_ashr_i32 s76, s46, 10
	s_lshl_b32 s47, s76, 1
	s_and_b32 s2, s46, 0x7f
	s_lshl_b32 s33, -1, s47
	s_andn2_b32 s50, s2, s33
	s_lshr_b32 s33, s2, s47
	s_lshl_b32 s77, s33, 7
	v_add_u32_e32 v142, s77, v112
	s_bfe_u32 s51, s46, 0x30007
	v_or_b32_e32 v0, v142, v109
	s_and_b32 s40, s46, 0xfffffc00
	s_lshl_b32 s2, s51, 7
	v_lshlrev_b32_e32 v0, s47, v0
	s_or_b32 s40, s2, s40
	v_add_u32_e32 v2, s50, v0
	v_mov_b64_e32 v[0:1], s[44:45]
	s_movk_i32 s41, 0x4800
	v_mad_i64_i32 v[0:1], s[78:79], v2, s41, v[0:1]
	s_ashr_i32 s41, s40, 31
	s_lshl_b64 s[40:41], s[40:41], 1
	v_lshl_add_u64 v[0:1], v[0:1], 0, s[40:41]
	v_lshl_add_u64 v[0:1], v[0:1], 0, v[168:169]
	global_load_dwordx4 v[96:99], v[0:1], off
	global_load_dwordx4 v[92:95], v[0:1], off offset:64
	global_load_dwordx4 v[88:91], v[0:1], off offset:128
	global_load_dwordx4 v[32:35], v[0:1], off offset:192
	s_addk_i32 s77, 0xff80
	s_add_u32 s78, s44, s40
	s_addc_u32 s79, s45, s41
	v_lshlrev_b32_e32 v36, 1, v108
	v_mov_b32_e32 v37, v169
	v_add_u32_e32 v1, s77, v118
	v_cmp_lt_i32_e32 vcc, -1, v1
	v_mov_b32_e32 v148, 0
	v_mov_b32_e32 v149, 0
	v_mov_b32_e32 v150, 0
	v_mov_b32_e32 v151, 0
	s_and_saveexec_b64 s[40:41], vcc
	s_cbranch_execz .Lattn_k0
	v_lshlrev_b32_e32 v1, s47, v1
	v_add_u32_e32 v1, s50, v1
	v_mov_b64_e32 v[2:3], s[78:79]
	s_movk_i32 s86, 0x4800
	v_mad_u64_u32 v[2:3], s[86:87], v1, s86, v[2:3]
	v_lshl_add_u64 v[2:3], v[2:3], 0, v[36:37]
	v_add_co_u32_e32 v2, vcc, 0x1000, v2
	s_nop 1
	v_addc_co_u32_e32 v3, vcc, 0, v3, vcc
	global_load_dwordx4 v[148:151], v[2:3], off offset:2048
.Lattn_k0:
	s_or_b64 exec, exec, s[40:41]
	v_add_u32_e32 v1, s77, v119
	v_cmp_lt_i32_e32 vcc, -1, v1
	v_mov_b32_e32 v152, 0
	v_mov_b32_e32 v153, 0
	v_mov_b32_e32 v154, 0
	v_mov_b32_e32 v155, 0
	s_and_saveexec_b64 s[40:41], vcc
	s_cbranch_execz .Lattn_k1
	v_lshlrev_b32_e32 v1, s47, v1
	v_add_u32_e32 v1, s50, v1
	v_mov_b64_e32 v[2:3], s[78:79]
	s_movk_i32 s86, 0x4800
	v_mad_u64_u32 v[2:3], s[86:87], v1, s86, v[2:3]
	v_lshl_add_u64 v[2:3], v[2:3], 0, v[36:37]
	v_add_co_u32_e32 v2, vcc, 0x1000, v2
	s_nop 1
	v_addc_co_u32_e32 v3, vcc, 0, v3, vcc
	global_load_dwordx4 v[152:155], v[2:3], off offset:2048
.Lattn_k1:
	s_or_b64 exec, exec, s[40:41]
	v_add_u32_e32 v1, s77, v120
	v_cmp_lt_i32_e32 vcc, -1, v1
	v_mov_b32_e32 v156, 0
	v_mov_b32_e32 v157, 0
	v_mov_b32_e32 v158, 0
	v_mov_b32_e32 v159, 0
	s_and_saveexec_b64 s[40:41], vcc
	s_cbranch_execz .Lattn_k2
	v_lshlrev_b32_e32 v1, s47, v1
	v_add_u32_e32 v1, s50, v1
	v_mov_b64_e32 v[2:3], s[78:79]
	s_movk_i32 s86, 0x4800
	v_mad_u64_u32 v[2:3], s[86:87], v1, s86, v[2:3]
	v_lshl_add_u64 v[2:3], v[2:3], 0, v[36:37]
	v_add_co_u32_e32 v2, vcc, 0x1000, v2
	s_nop 1
	v_addc_co_u32_e32 v3, vcc, 0, v3, vcc
	global_load_dwordx4 v[156:159], v[2:3], off offset:2048
.Lattn_k2:
	s_or_b64 exec, exec, s[40:41]
	v_add_u32_e32 v1, s77, v121
	v_cmp_lt_i32_e32 vcc, -1, v1
	v_mov_b32_e32 v160, 0
	v_mov_b32_e32 v161, 0
	v_mov_b32_e32 v162, 0
	v_mov_b32_e32 v163, 0
	s_and_saveexec_b64 s[40:41], vcc
	s_cbranch_execz .Lattn_k3
	v_lshlrev_b32_e32 v1, s47, v1
	v_add_u32_e32 v1, s50, v1
	v_mov_b64_e32 v[2:3], s[78:79]
	s_movk_i32 s86, 0x4800
	v_mad_u64_u32 v[2:3], s[86:87], v1, s86, v[2:3]
	v_lshl_add_u64 v[2:3], v[2:3], 0, v[36:37]
	v_add_co_u32_e32 v2, vcc, 0x1000, v2
	s_nop 1
	v_addc_co_u32_e32 v3, vcc, 0, v3, vcc
	global_load_dwordx4 v[160:163], v[2:3], off offset:2048
.Lattn_k3:
	s_or_b64 exec, exec, s[40:41]
	v_add_u32_e32 v1, s77, v122
	v_cmp_lt_i32_e32 vcc, -1, v1
	v_mov_b32_e32 v176, 0
	v_mov_b32_e32 v177, 0
	v_mov_b32_e32 v178, 0
	v_mov_b32_e32 v179, 0
	s_and_saveexec_b64 s[40:41], vcc
	s_cbranch_execz .Lattn_k4
	v_lshlrev_b32_e32 v1, s47, v1
	v_add_u32_e32 v1, s50, v1
	v_mov_b64_e32 v[2:3], s[78:79]
	s_movk_i32 s86, 0x4800
	v_mad_u64_u32 v[2:3], s[86:87], v1, s86, v[2:3]
	v_lshl_add_u64 v[2:3], v[2:3], 0, v[36:37]
	v_add_co_u32_e32 v2, vcc, 0x1000, v2
	s_nop 1
	v_addc_co_u32_e32 v3, vcc, 0, v3, vcc
	global_load_dwordx4 v[176:179], v[2:3], off offset:2048
.Lattn_k4:
	s_or_b64 exec, exec, s[40:41]
	v_add_u32_e32 v1, s77, v123
	v_cmp_lt_i32_e32 vcc, -1, v1
	v_mov_b32_e32 v180, 0
	v_mov_b32_e32 v181, 0
	v_mov_b32_e32 v182, 0
	v_mov_b32_e32 v183, 0
	s_and_saveexec_b64 s[40:41], vcc
	s_cbranch_execz .Lattn_k5
	v_lshlrev_b32_e32 v1, s47, v1
	v_add_u32_e32 v1, s50, v1
	v_mov_b64_e32 v[2:3], s[78:79]
	s_movk_i32 s86, 0x4800
	v_mad_u64_u32 v[2:3], s[86:87], v1, s86, v[2:3]
	v_lshl_add_u64 v[2:3], v[2:3], 0, v[36:37]
	v_add_co_u32_e32 v2, vcc, 0x1000, v2
	s_nop 1
	v_addc_co_u32_e32 v3, vcc, 0, v3, vcc
	global_load_dwordx4 v[180:183], v[2:3], off offset:2048
.Lattn_k5:
	s_or_b64 exec, exec, s[40:41]
	v_add_u32_e32 v1, s77, v124
	v_cmp_lt_i32_e32 vcc, -1, v1
	v_mov_b32_e32 v184, 0
	v_mov_b32_e32 v185, 0
	v_mov_b32_e32 v186, 0
	v_mov_b32_e32 v187, 0
	s_and_saveexec_b64 s[40:41], vcc
	s_cbranch_execz .Lattn_k6
	v_lshlrev_b32_e32 v1, s47, v1
	v_add_u32_e32 v1, s50, v1
	v_mov_b64_e32 v[2:3], s[78:79]
	s_movk_i32 s86, 0x4800
	v_mad_u64_u32 v[2:3], s[86:87], v1, s86, v[2:3]
	v_lshl_add_u64 v[2:3], v[2:3], 0, v[36:37]
	v_add_co_u32_e32 v2, vcc, 0x1000, v2
	s_nop 1
	v_addc_co_u32_e32 v3, vcc, 0, v3, vcc
	global_load_dwordx4 v[184:187], v[2:3], off offset:2048
.Lattn_k6:
	s_or_b64 exec, exec, s[40:41]
	v_add_u32_e32 v1, s77, v125
	v_cmp_lt_i32_e32 vcc, -1, v1
	v_mov_b32_e32 v188, 0
	v_mov_b32_e32 v189, 0
	v_mov_b32_e32 v190, 0
	v_mov_b32_e32 v191, 0
	s_and_saveexec_b64 s[40:41], vcc
	s_cbranch_execz .Lattn_k7
	v_lshlrev_b32_e32 v1, s47, v1
	v_add_u32_e32 v1, s50, v1
	v_mov_b64_e32 v[2:3], s[78:79]
	s_movk_i32 s86, 0x4800
	v_mad_u64_u32 v[2:3], s[86:87], v1, s86, v[2:3]
	v_lshl_add_u64 v[2:3], v[2:3], 0, v[36:37]
	v_add_co_u32_e32 v2, vcc, 0x1000, v2
	s_nop 1
	v_addc_co_u32_e32 v3, vcc, 0, v3, vcc
	global_load_dwordx4 v[188:191], v[2:3], off offset:2048
.Lattn_k7:
	s_or_b64 exec, exec, s[40:41]
	v_add_u32_e32 v38, s77, v113
	s_waitcnt vmcnt(0)
	ds_write_b128 v131, v[148:151]
	ds_write_b128 v132, v[152:155]
	ds_write_b128 v133, v[156:159]
	ds_write_b128 v134, v[160:163]
	ds_write_b128 v135, v[176:179]
	ds_write_b128 v136, v[180:183]
	ds_write_b128 v137, v[184:187]
	ds_write_b128 v138, v[188:191]
	v_cmp_lt_i32_e64 s[40:41], -1, v38
	v_mov_b32_e32 v0, 0
	v_mov_b32_e32 v4, 0
	v_mov_b32_e32 v5, 0
	v_mov_b32_e32 v6, 0
	v_mov_b32_e32 v7, 0
	s_and_saveexec_b64 s[86:87], s[40:41]
	s_cbranch_execz .LBB0_196
	v_lshlrev_b32_e32 v1, s47, v38
	v_add_u32_e32 v1, s50, v1
	v_mov_b64_e32 v[2:3], s[78:79]
	s_movk_i32 s77, 0x4800
	v_mad_u64_u32 v[2:3], vcc, v1, s77, v[2:3]
	v_mov_b32_e32 v37, v169
	v_lshl_add_u64 v[2:3], v[2:3], 0, v[36:37]
	v_add_co_u32_e32 v2, vcc, 0x3000, v2
	s_nop 1
	v_addc_co_u32_e32 v3, vcc, 0, v3, vcc
	global_load_dwordx4 v[4:7], v[2:3], off

; #define PG8_BAR __builtin_amdgcn_s_barrier()
; template <class Epi>
; __device__ __forceinline__ void gemm_phase(LAS unsigned char* lds, const Gemm g, const StaticOrder& S, const Epi& E) {
;     ...
; #pragma unroll
;         for (int a = 0; a < 2; ++a)
; #pragma unroll
;             for (int b = 0; b < 2; ++b)
; #pragma unroll
;                 for (int m = 0; m < 4; ++m)
; #pragma unroll
;                     for (int n = 0; n < 2; ++n) acc[a][b][m][n] = (f32x4){0.f, 0.f, 0.f, 0.f};
;         cur = nxt; cA = nA; cB = nB; ++ui;
;         if (wr == 1) PG8_BAR;
.LBB0_341:
	s_add_u32 s4, s36, 0x80
	s_addc_u32 s5, s37, 0
	s_add_u32 s36, s34, 0x100
	v_mov_b32_e32 v0, 0
	s_addc_u32 s37, s35, 0
	s_mov_b32 s34, 0
	s_waitcnt lgkmcnt(0)
	v_mov_b32_e32 v1, v0
	v_mov_b32_e32 v2, v0
	v_mov_b32_e32 v3, v0
	v_mov_b32_e32 v4, v0
	v_mov_b32_e32 v5, v0
	v_mov_b32_e32 v6, v0
	v_mov_b32_e32 v7, v0
	v_mov_b32_e32 v12, v0
	v_mov_b32_e32 v13, v0
	v_mov_b32_e32 v14, v0
	v_mov_b32_e32 v15, v0
	v_mov_b32_e32 v20, v0
	v_mov_b32_e32 v21, v0
	s_nop 0
	v_mov_b32_e32 v22, v0
	v_mov_b32_e32 v23, v0
	v_mov_b32_e32 v28, v0
	v_mov_b32_e32 v29, v0
	v_mov_b32_e32 v30, v0
	v_mov_b32_e32 v31, v0
	v_mov_b32_e32 v36, v0
	v_mov_b32_e32 v37, v0
	v_mov_b32_e32 v38, v0
	v_mov_b32_e32 v39, v0
	v_mov_b32_e32 v44, v0
	v_mov_b32_e32 v45, v0
	v_mov_b32_e32 v46, v0
	v_mov_b32_e32 v47, v0
	v_mov_b32_e32 v52, v0
	v_mov_b32_e32 v53, v0
	v_mov_b32_e32 v54, v0
	v_mov_b32_e32 v55, v0
	v_mov_b32_e32 v8, v0
	v_mov_b32_e32 v9, v0
	v_mov_b32_e32 v10, v0
	v_mov_b32_e32 v11, v0
	v_mov_b32_e32 v16, v0
	v_mov_b32_e32 v17, v0
	v_mov_b32_e32 v18, v0
	v_mov_b32_e32 v19, v0
	v_mov_b32_e32 v24, v0
	v_mov_b32_e32 v25, v0
	v_mov_b32_e32 v26, v0
	v_mov_b32_e32 v27, v0
	v_mov_b32_e32 v32, v0
	v_mov_b32_e32 v33, v0
	v_mov_b32_e32 v34, v0
	v_mov_b32_e32 v35, v0
	v_mov_b32_e32 v40, v0
	v_mov_b32_e32 v41, v0
	v_mov_b32_e32 v42, v0
	v_mov_b32_e32 v43, v0
	v_mov_b32_e32 v48, v0
	v_mov_b32_e32 v49, v0
	v_mov_b32_e32 v50, v0
	v_mov_b32_e32 v51, v0
	v_mov_b32_e32 v56, v0
	v_mov_b32_e32 v57, v0
	v_mov_b32_e32 v58, v0
	v_mov_b32_e32 v59, v0
	v_mov_b32_e32 v60, v0
	v_mov_b32_e32 v61, v0
	v_mov_b32_e32 v62, v0
	v_mov_b32_e32 v63, v0
	v_mov_b32_e32 v64, v0
	v_mov_b32_e32 v65, v0
	v_mov_b32_e32 v66, v0
	v_mov_b32_e32 v67, v0
	v_mov_b32_e32 v68, v0
	v_mov_b32_e32 v69, v0
	v_mov_b32_e32 v70, v0
	v_mov_b32_e32 v71, v0
	v_mov_b32_e32 v76, v0
	v_mov_b32_e32 v77, v0
	v_mov_b32_e32 v78, v0
	v_mov_b32_e32 v79, v0
	v_mov_b32_e32 v84, v0
	v_mov_b32_e32 v85, v0
	v_mov_b32_e32 v86, v0
	v_mov_b32_e32 v87, v0
	v_mov_b32_e32 v92, v0
	v_mov_b32_e32 v93, v0
	v_mov_b32_e32 v94, v0
	v_mov_b32_e32 v95, v0
	v_mov_b32_e32 v100, v0
	v_mov_b32_e32 v101, v0
	v_mov_b32_e32 v102, v0
	v_mov_b32_e32 v103, v0
	v_mov_b32_e32 v108, v0
	v_mov_b32_e32 v109, v0
	v_mov_b32_e32 v110, v0
	v_mov_b32_e32 v111, v0
	v_mov_b32_e32 v116, v0
	v_mov_b32_e32 v117, v0
	v_mov_b32_e32 v118, v0
	v_mov_b32_e32 v119, v0
	v_mov_b32_e32 v72, v0
	v_mov_b32_e32 v73, v0
	v_mov_b32_e32 v74, v0
	v_mov_b32_e32 v75, v0
	v_mov_b32_e32 v80, v0
	v_mov_b32_e32 v81, v0
	v_mov_b32_e32 v82, v0
	v_mov_b32_e32 v83, v0
	v_mov_b32_e32 v88, v0
	v_mov_b32_e32 v89, v0
	v_mov_b32_e32 v90, v0
	v_mov_b32_e32 v91, v0
	v_mov_b32_e32 v96, v0
	v_mov_b32_e32 v97, v0
	v_mov_b32_e32 v98, v0
	v_mov_b32_e32 v99, v0
	v_mov_b32_e32 v104, v0
	v_mov_b32_e32 v105, v0
	v_mov_b32_e32 v106, v0
	v_mov_b32_e32 v107, v0
	v_mov_b32_e32 v112, v0
	v_mov_b32_e32 v113, v0
	v_mov_b32_e32 v114, v0
	v_mov_b32_e32 v115, v0
	v_mov_b32_e32 v120, v0
	v_mov_b32_e32 v121, v0
	v_mov_b32_e32 v122, v0
	v_mov_b32_e32 v123, v0
	v_mov_b32_e32 v124, v0
	v_mov_b32_e32 v125, v0
	v_mov_b32_e32 v126, v0
	v_mov_b32_e32 v127, v0

; #define PG8_BAR __builtin_amdgcn_s_barrier()
; template <class Epi>
; __device__ __forceinline__ void gemm_phase(LAS unsigned char* lds, const Gemm g, const StaticOrder& S, const Epi& E) {
;     ...
; #pragma unroll
;         for (int a = 0; a < 2; ++a)
; #pragma unroll
;             for (int b = 0; b < 2; ++b)
; #pragma unroll
;                 for (int m = 0; m < 4; ++m)
; #pragma unroll
;                     for (int n = 0; n < 2; ++n) acc[a][b][m][n] = (f32x4){0.f, 0.f, 0.f, 0.f};
;         cur = nxt; cA = nA; cB = nB; ++ui;
;         if (wr == 1) PG8_BAR;
.LBB0_430:
	s_add_u32 s0, s40, 0x80080
	s_addc_u32 s1, s41, 0
	s_add_u32 s29, s38, 0x100
	v_mov_b32_e32 v0, 0
	s_addc_u32 s33, s39, 0
	s_mov_b32 s37, 0
	v_mov_b32_e32 v1, v0
	v_mov_b32_e32 v2, v0
	v_mov_b32_e32 v3, v0
	v_mov_b32_e32 v4, v0
	v_mov_b32_e32 v5, v0
	v_mov_b32_e32 v6, v0
	v_mov_b32_e32 v7, v0
	v_mov_b32_e32 v16, v0
	v_mov_b32_e32 v17, v0
	v_mov_b32_e32 v18, v0
	v_mov_b32_e32 v19, v0
	v_mov_b32_e32 v20, v0
	v_mov_b32_e32 v21, v0
	s_nop 0
	v_mov_b32_e32 v22, v0
	v_mov_b32_e32 v23, v0
	v_mov_b32_e32 v32, v0
	v_mov_b32_e32 v33, v0
	v_mov_b32_e32 v34, v0
	v_mov_b32_e32 v35, v0
	v_mov_b32_e32 v36, v0
	v_mov_b32_e32 v37, v0
	v_mov_b32_e32 v38, v0
	v_mov_b32_e32 v39, v0
	v_mov_b32_e32 v48, v0
	v_mov_b32_e32 v49, v0
	v_mov_b32_e32 v50, v0
	v_mov_b32_e32 v51, v0
	v_mov_b32_e32 v52, v0
	v_mov_b32_e32 v53, v0
	v_mov_b32_e32 v54, v0
	v_mov_b32_e32 v55, v0
	v_mov_b32_e32 v8, v0
	v_mov_b32_e32 v9, v0
	v_mov_b32_e32 v10, v0
	v_mov_b32_e32 v11, v0
	v_mov_b32_e32 v12, v0
	v_mov_b32_e32 v13, v0
	v_mov_b32_e32 v14, v0
	v_mov_b32_e32 v15, v0
	v_mov_b32_e32 v24, v0
	v_mov_b32_e32 v25, v0
	v_mov_b32_e32 v26, v0
	v_mov_b32_e32 v27, v0
	v_mov_b32_e32 v28, v0
	v_mov_b32_e32 v29, v0
	v_mov_b32_e32 v30, v0
	v_mov_b32_e32 v31, v0
	v_mov_b32_e32 v40, v0
	v_mov_b32_e32 v41, v0
	v_mov_b32_e32 v42, v0
	v_mov_b32_e32 v43, v0
	v_mov_b32_e32 v44, v0
	v_mov_b32_e32 v45, v0
	v_mov_b32_e32 v46, v0
	v_mov_b32_e32 v47, v0
	v_mov_b32_e32 v56, v0
	v_mov_b32_e32 v57, v0
	v_mov_b32_e32 v58, v0
	v_mov_b32_e32 v59, v0
	v_mov_b32_e32 v60, v0
	v_mov_b32_e32 v61, v0
	v_mov_b32_e32 v62, v0
	v_mov_b32_e32 v63, v0
	v_mov_b32_e32 v64, v0
	v_mov_b32_e32 v65, v0
	v_mov_b32_e32 v66, v0
	v_mov_b32_e32 v67, v0
	v_mov_b32_e32 v68, v0
	v_mov_b32_e32 v69, v0
	v_mov_b32_e32 v70, v0
	v_mov_b32_e32 v71, v0
	v_mov_b32_e32 v80, v0
	v_mov_b32_e32 v81, v0
	v_mov_b32_e32 v82, v0
	v_mov_b32_e32 v83, v0
	v_mov_b32_e32 v84, v0
	v_mov_b32_e32 v85, v0
	v_mov_b32_e32 v86, v0
	v_mov_b32_e32 v87, v0
	v_mov_b32_e32 v96, v0
	v_mov_b32_e32 v97, v0
	v_mov_b32_e32 v98, v0
	v_mov_b32_e32 v99, v0
	v_mov_b32_e32 v100, v0
	v_mov_b32_e32 v101, v0
	v_mov_b32_e32 v102, v0
	v_mov_b32_e32 v103, v0
	v_mov_b32_e32 v112, v0
	v_mov_b32_e32 v113, v0
	v_mov_b32_e32 v114, v0
	v_mov_b32_e32 v115, v0
	v_mov_b32_e32 v116, v0
	v_mov_b32_e32 v117, v0
	v_mov_b32_e32 v118, v0
	v_mov_b32_e32 v119, v0
	v_mov_b32_e32 v72, v0
	v_mov_b32_e32 v73, v0
	v_mov_b32_e32 v74, v0
	v_mov_b32_e32 v75, v0
	v_mov_b32_e32 v76, v0
	v_mov_b32_e32 v77, v0
	v_mov_b32_e32 v78, v0
	v_mov_b32_e32 v79, v0
	v_mov_b32_e32 v88, v0
	v_mov_b32_e32 v89, v0
	v_mov_b32_e32 v90, v0
	v_mov_b32_e32 v91, v0
	v_mov_b32_e32 v92, v0
	v_mov_b32_e32 v93, v0
	v_mov_b32_e32 v94, v0
	v_mov_b32_e32 v95, v0
	v_mov_b32_e32 v104, v0
	v_mov_b32_e32 v105, v0
	v_mov_b32_e32 v106, v0
	v_mov_b32_e32 v107, v0
	v_mov_b32_e32 v108, v0
	v_mov_b32_e32 v109, v0
	v_mov_b32_e32 v110, v0
	v_mov_b32_e32 v111, v0
	v_mov_b32_e32 v120, v0
	v_mov_b32_e32 v121, v0
	v_mov_b32_e32 v122, v0
	v_mov_b32_e32 v123, v0
	v_mov_b32_e32 v124, v0
	v_mov_b32_e32 v125, v0
	v_mov_b32_e32 v126, v0
	v_mov_b32_e32 v127, v0
